# P0: adaLN GEMV loads issued up front with counted waits; rg_wa/rg_wx transpose item pipelined with 16-byte loads
# speedup vs baseline: 1.0262x; 1.0262x over previous
.LBB0_425:
	s_andn2_b64 vcc, exec, s[0:1]
	s_cbranch_vccnz .LBB0_432
	s_and_saveexec_b64 s[14:15], s[36:37]
	v_readlane_b32 s52, v255, 12
	v_readlane_b32 s53, v255, 13
	v_readlane_b32 s56, v255, 16
	v_readlane_b32 s57, v255, 17
	v_readlane_b32 s54, v255, 14
	v_readlane_b32 s55, v255, 15
	v_readlane_b32 s58, v255, 18
	v_readlane_b32 s59, v255, 19
	v_readlane_b32 s60, v255, 20
	v_readlane_b32 s61, v255, 21
	v_readlane_b32 s62, v255, 22
	v_readlane_b32 s63, v255, 23
	v_readlane_b32 s64, v255, 24
	v_readlane_b32 s65, v255, 25
	v_readlane_b32 s66, v255, 26
	v_readlane_b32 s67, v255, 27
	s_cbranch_execz .LBB0_429
	v_lshlrev_b32_e32 v84, 8, v52
	v_lshrrev_b32_e32 v85, 6, v38
	v_lshl_add_u32 v84, v85, 5, v84
	v_mul_u32_u24_e32 v86, 0x380, v85
	v_add_co_u32_e32 v100, vcc, v44, v86
	s_nop 1
	v_addc_co_u32_e32 v101, vcc, 0, v45, vcc
	v_add_co_u32_e32 v102, vcc, 0x10000, v100
	s_nop 1
	v_addc_co_u32_e32 v103, vcc, 0, v101, vcc
	s_mov_b64 s[16:17], s[52:53]
	s_mov_b64 s[0:1], s[56:57]
	global_load_dwordx4 v[104:107], v84, s[16:17]
	global_load_dwordx4 v[108:111], v84, s[16:17] offset:16
	global_load_dwordx4 v[112:115], v84, s[0:1]
	global_load_dwordx4 v[116:119], v84, s[0:1] offset:16
	s_add_u32 s16, s16, 0x4000
	s_addc_u32 s17, s17, 0
	s_add_u32 s0, s0, 0x4000
	s_addc_u32 s1, s1, 0
	global_load_dwordx4 v[120:123], v84, s[16:17]
	global_load_dwordx4 v[124:127], v84, s[16:17] offset:16
	global_load_dwordx4 v[128:131], v84, s[0:1]
	global_load_dwordx4 v[132:135], v84, s[0:1] offset:16
	s_add_u32 s16, s16, 0x4000
	s_addc_u32 s17, s17, 0
	s_add_u32 s0, s0, 0x4000
	s_addc_u32 s1, s1, 0
	global_load_dwordx4 v[136:139], v84, s[16:17]
	global_load_dwordx4 v[140:143], v84, s[16:17] offset:16
	global_load_dwordx4 v[144:147], v84, s[0:1]
	global_load_dwordx4 v[148:151], v84, s[0:1] offset:16
	s_add_u32 s16, s16, 0x4000
	s_addc_u32 s17, s17, 0
	s_add_u32 s0, s0, 0x4000
	s_addc_u32 s1, s1, 0
	global_load_dwordx4 v[152:155], v84, s[16:17]
	global_load_dwordx4 v[156:159], v84, s[16:17] offset:16
	global_load_dwordx4 v[160:163], v84, s[0:1]
	global_load_dwordx4 v[164:167], v84, s[0:1] offset:16
	s_add_u32 s16, s16, 0x4000
	s_addc_u32 s17, s17, 0
	s_add_u32 s0, s0, 0x4000
	s_addc_u32 s1, s1, 0
	global_load_dwordx4 v[168:171], v84, s[16:17]
	global_load_dwordx4 v[172:175], v84, s[16:17] offset:16
	global_load_dwordx4 v[176:179], v84, s[0:1]
	global_load_dwordx4 v[180:183], v84, s[0:1] offset:16
	s_add_u32 s16, s16, 0x4000
	s_addc_u32 s17, s17, 0
	s_add_u32 s0, s0, 0x4000
	s_addc_u32 s1, s1, 0
	global_load_dwordx4 v[184:187], v84, s[16:17]
	global_load_dwordx4 v[188:191], v84, s[16:17] offset:16
	global_load_dwordx4 v[192:195], v84, s[0:1]
	global_load_dwordx4 v[2:5], v84, s[0:1] offset:16
	s_add_u32 s16, s16, 0x4000
	s_addc_u32 s17, s17, 0
	s_add_u32 s0, s0, 0x4000
	s_addc_u32 s1, s1, 0
	s_waitcnt vmcnt(16)
	v_cvt_pk_bf16_f32 v104, v104, v196
	v_cvt_pk_bf16_f32 v105, v105, v196
	v_cvt_pk_bf16_f32 v106, v106, v196
	v_cvt_pk_bf16_f32 v107, v107, v196
	v_cvt_pk_bf16_f32 v108, v108, v196
	v_cvt_pk_bf16_f32 v109, v109, v196
	v_cvt_pk_bf16_f32 v110, v110, v196
	v_cvt_pk_bf16_f32 v111, v111, v196
	v_cvt_pk_bf16_f32 v112, v112, v196
	v_cvt_pk_bf16_f32 v113, v113, v196
	v_cvt_pk_bf16_f32 v114, v114, v196
	v_cvt_pk_bf16_f32 v115, v115, v196
	v_cvt_pk_bf16_f32 v116, v116, v196
	v_cvt_pk_bf16_f32 v117, v117, v196
	v_cvt_pk_bf16_f32 v118, v118, v196
	v_cvt_pk_bf16_f32 v119, v119, v196
	global_store_short v[100:101], v104, off
	global_store_short v[100:101], v105, off offset:128
	global_store_short v[100:101], v106, off offset:256
	global_store_short v[100:101], v107, off offset:384
	global_store_short v[100:101], v108, off offset:512
	global_store_short v[100:101], v109, off offset:640
	global_store_short v[100:101], v110, off offset:768
	global_store_short v[100:101], v111, off offset:896
	global_store_short v[102:103], v112, off
	global_store_short v[102:103], v113, off offset:128
	global_store_short v[102:103], v114, off offset:256
	global_store_short v[102:103], v115, off offset:384
	global_store_short v[102:103], v116, off offset:512
	global_store_short v[102:103], v117, off offset:640
	global_store_short v[102:103], v118, off offset:768
	global_store_short v[102:103], v119, off offset:896
	v_add_co_u32_e32 v100, vcc, 0x2000, v100
	s_nop 1
	v_addc_co_u32_e32 v101, vcc, 0, v101, vcc
	v_add_co_u32_e32 v102, vcc, 0x2000, v102
	s_nop 1
	v_addc_co_u32_e32 v103, vcc, 0, v103, vcc
	v_cvt_pk_bf16_f32 v120, v120, v196
	v_cvt_pk_bf16_f32 v121, v121, v196
	v_cvt_pk_bf16_f32 v122, v122, v196
	v_cvt_pk_bf16_f32 v123, v123, v196
	v_cvt_pk_bf16_f32 v124, v124, v196
	v_cvt_pk_bf16_f32 v125, v125, v196
	v_cvt_pk_bf16_f32 v126, v126, v196
	v_cvt_pk_bf16_f32 v127, v127, v196
	v_cvt_pk_bf16_f32 v128, v128, v196
	v_cvt_pk_bf16_f32 v129, v129, v196
	v_cvt_pk_bf16_f32 v130, v130, v196
	v_cvt_pk_bf16_f32 v131, v131, v196
	v_cvt_pk_bf16_f32 v132, v132, v196
	v_cvt_pk_bf16_f32 v133, v133, v196
	v_cvt_pk_bf16_f32 v134, v134, v196
	v_cvt_pk_bf16_f32 v135, v135, v196
	global_store_short v[100:101], v120, off
	global_store_short v[100:101], v121, off offset:128
	global_store_short v[100:101], v122, off offset:256
	global_store_short v[100:101], v123, off offset:384
	global_store_short v[100:101], v124, off offset:512
	global_store_short v[100:101], v125, off offset:640
	global_store_short v[100:101], v126, off offset:768
	global_store_short v[100:101], v127, off offset:896
	global_store_short v[102:103], v128, off
	global_store_short v[102:103], v129, off offset:128
	global_store_short v[102:103], v130, off offset:256
	global_store_short v[102:103], v131, off offset:384
	global_store_short v[102:103], v132, off offset:512
	global_store_short v[102:103], v133, off offset:640
	global_store_short v[102:103], v134, off offset:768
	global_store_short v[102:103], v135, off offset:896
	v_add_co_u32_e32 v100, vcc, 0x2000, v100
	s_nop 1
	v_addc_co_u32_e32 v101, vcc, 0, v101, vcc
	v_add_co_u32_e32 v102, vcc, 0x2000, v102
	s_nop 1
	v_addc_co_u32_e32 v103, vcc, 0, v103, vcc
	global_load_dwordx4 v[104:107], v84, s[16:17]
	global_load_dwordx4 v[108:111], v84, s[16:17] offset:16
	global_load_dwordx4 v[112:115], v84, s[0:1]
	global_load_dwordx4 v[116:119], v84, s[0:1] offset:16
	s_add_u32 s16, s16, 0x4000
	s_addc_u32 s17, s17, 0
	s_add_u32 s0, s0, 0x4000
	s_addc_u32 s1, s1, 0
	global_load_dwordx4 v[120:123], v84, s[16:17]
	global_load_dwordx4 v[124:127], v84, s[16:17] offset:16
	global_load_dwordx4 v[128:131], v84, s[0:1]
	global_load_dwordx4 v[132:135], v84, s[0:1] offset:16
	s_waitcnt vmcnt(48)
	v_cvt_pk_bf16_f32 v136, v136, v196
	v_cvt_pk_bf16_f32 v137, v137, v196
	v_cvt_pk_bf16_f32 v138, v138, v196
	v_cvt_pk_bf16_f32 v139, v139, v196
	v_cvt_pk_bf16_f32 v140, v140, v196
	v_cvt_pk_bf16_f32 v141, v141, v196
	v_cvt_pk_bf16_f32 v142, v142, v196
	v_cvt_pk_bf16_f32 v143, v143, v196
	v_cvt_pk_bf16_f32 v144, v144, v196
	v_cvt_pk_bf16_f32 v145, v145, v196
	v_cvt_pk_bf16_f32 v146, v146, v196
	v_cvt_pk_bf16_f32 v147, v147, v196
	v_cvt_pk_bf16_f32 v148, v148, v196
	v_cvt_pk_bf16_f32 v149, v149, v196
	v_cvt_pk_bf16_f32 v150, v150, v196
	v_cvt_pk_bf16_f32 v151, v151, v196
	global_store_short v[100:101], v136, off
	global_store_short v[100:101], v137, off offset:128
	global_store_short v[100:101], v138, off offset:256
	global_store_short v[100:101], v139, off offset:384
	global_store_short v[100:101], v140, off offset:512
	global_store_short v[100:101], v141, off offset:640
	global_store_short v[100:101], v142, off offset:768
	global_store_short v[100:101], v143, off offset:896
	global_store_short v[102:103], v144, off
	global_store_short v[102:103], v145, off offset:128
	global_store_short v[102:103], v146, off offset:256
	global_store_short v[102:103], v147, off offset:384
	global_store_short v[102:103], v148, off offset:512
	global_store_short v[102:103], v149, off offset:640
	global_store_short v[102:103], v150, off offset:768
	global_store_short v[102:103], v151, off offset:896
	v_add_co_u32_e32 v100, vcc, 0x2000, v100
	s_nop 1
	v_addc_co_u32_e32 v101, vcc, 0, v101, vcc
	v_add_co_u32_e32 v102, vcc, 0x2000, v102
	s_nop 1
	v_addc_co_u32_e32 v103, vcc, 0, v103, vcc
	v_cvt_pk_bf16_f32 v152, v152, v196
	v_cvt_pk_bf16_f32 v153, v153, v196
	v_cvt_pk_bf16_f32 v154, v154, v196
	v_cvt_pk_bf16_f32 v155, v155, v196
	v_cvt_pk_bf16_f32 v156, v156, v196
	v_cvt_pk_bf16_f32 v157, v157, v196
	v_cvt_pk_bf16_f32 v158, v158, v196
	v_cvt_pk_bf16_f32 v159, v159, v196
	v_cvt_pk_bf16_f32 v160, v160, v196
	v_cvt_pk_bf16_f32 v161, v161, v196
	v_cvt_pk_bf16_f32 v162, v162, v196
	v_cvt_pk_bf16_f32 v163, v163, v196
	v_cvt_pk_bf16_f32 v164, v164, v196
	v_cvt_pk_bf16_f32 v165, v165, v196
	v_cvt_pk_bf16_f32 v166, v166, v196
	v_cvt_pk_bf16_f32 v167, v167, v196
	global_store_short v[100:101], v152, off
	global_store_short v[100:101], v153, off offset:128
	global_store_short v[100:101], v154, off offset:256
	global_store_short v[100:101], v155, off offset:384
	global_store_short v[100:101], v156, off offset:512
	global_store_short v[100:101], v157, off offset:640
	global_store_short v[100:101], v158, off offset:768
	global_store_short v[100:101], v159, off offset:896
	global_store_short v[102:103], v160, off
	global_store_short v[102:103], v161, off offset:128
	global_store_short v[102:103], v162, off offset:256
	global_store_short v[102:103], v163, off offset:384
	global_store_short v[102:103], v164, off offset:512
	global_store_short v[102:103], v165, off offset:640
	global_store_short v[102:103], v166, off offset:768
	global_store_short v[102:103], v167, off offset:896
	v_add_co_u32_e32 v100, vcc, 0x2000, v100
	s_nop 1
	v_addc_co_u32_e32 v101, vcc, 0, v101, vcc
	v_add_co_u32_e32 v102, vcc, 0x2000, v102
	s_nop 1
	v_addc_co_u32_e32 v103, vcc, 0, v103, vcc
	s_waitcnt vmcnt(56)
	v_cvt_pk_bf16_f32 v168, v168, v196
	v_cvt_pk_bf16_f32 v169, v169, v196
	v_cvt_pk_bf16_f32 v170, v170, v196
	v_cvt_pk_bf16_f32 v171, v171, v196
	v_cvt_pk_bf16_f32 v172, v172, v196
	v_cvt_pk_bf16_f32 v173, v173, v196
	v_cvt_pk_bf16_f32 v174, v174, v196
	v_cvt_pk_bf16_f32 v175, v175, v196
	v_cvt_pk_bf16_f32 v176, v176, v196
	v_cvt_pk_bf16_f32 v177, v177, v196
	v_cvt_pk_bf16_f32 v178, v178, v196
	v_cvt_pk_bf16_f32 v179, v179, v196
	v_cvt_pk_bf16_f32 v180, v180, v196
	v_cvt_pk_bf16_f32 v181, v181, v196
	v_cvt_pk_bf16_f32 v182, v182, v196
	v_cvt_pk_bf16_f32 v183, v183, v196
	global_store_short v[100:101], v168, off
	global_store_short v[100:101], v169, off offset:128
	global_store_short v[100:101], v170, off offset:256
	global_store_short v[100:101], v171, off offset:384
	global_store_short v[100:101], v172, off offset:512
	global_store_short v[100:101], v173, off offset:640
	global_store_short v[100:101], v174, off offset:768
	global_store_short v[100:101], v175, off offset:896
	global_store_short v[102:103], v176, off
	global_store_short v[102:103], v177, off offset:128
	global_store_short v[102:103], v178, off offset:256
	global_store_short v[102:103], v179, off offset:384
	global_store_short v[102:103], v180, off offset:512
	global_store_short v[102:103], v181, off offset:640
	global_store_short v[102:103], v182, off offset:768
	global_store_short v[102:103], v183, off offset:896
	v_add_co_u32_e32 v100, vcc, 0x2000, v100
	s_nop 1
	v_addc_co_u32_e32 v101, vcc, 0, v101, vcc
	v_add_co_u32_e32 v102, vcc, 0x2000, v102
	s_nop 1
	v_addc_co_u32_e32 v103, vcc, 0, v103, vcc
	v_cvt_pk_bf16_f32 v184, v184, v196
	v_cvt_pk_bf16_f32 v185, v185, v196
	v_cvt_pk_bf16_f32 v186, v186, v196
	v_cvt_pk_bf16_f32 v187, v187, v196
	v_cvt_pk_bf16_f32 v188, v188, v196
	v_cvt_pk_bf16_f32 v189, v189, v196
	v_cvt_pk_bf16_f32 v190, v190, v196
	v_cvt_pk_bf16_f32 v191, v191, v196
	v_cvt_pk_bf16_f32 v192, v192, v196
	v_cvt_pk_bf16_f32 v193, v193, v196
	v_cvt_pk_bf16_f32 v194, v194, v196
	v_cvt_pk_bf16_f32 v195, v195, v196
	v_cvt_pk_bf16_f32 v2, v2, v196
	v_cvt_pk_bf16_f32 v3, v3, v196
	v_cvt_pk_bf16_f32 v4, v4, v196
	v_cvt_pk_bf16_f32 v5, v5, v196
	global_store_short v[100:101], v184, off
	global_store_short v[100:101], v185, off offset:128
	global_store_short v[100:101], v186, off offset:256
	global_store_short v[100:101], v187, off offset:384
	global_store_short v[100:101], v188, off offset:512
	global_store_short v[100:101], v189, off offset:640
	global_store_short v[100:101], v190, off offset:768
	global_store_short v[100:101], v191, off offset:896
	global_store_short v[102:103], v192, off
	global_store_short v[102:103], v193, off offset:128
	global_store_short v[102:103], v194, off offset:256
	global_store_short v[102:103], v195, off offset:384
	global_store_short v[102:103], v2, off offset:512
	global_store_short v[102:103], v3, off offset:640
	global_store_short v[102:103], v4, off offset:768
	global_store_short v[102:103], v5, off offset:896
	v_add_co_u32_e32 v100, vcc, 0x2000, v100
	s_nop 1
	v_addc_co_u32_e32 v101, vcc, 0, v101, vcc
	v_add_co_u32_e32 v102, vcc, 0x2000, v102
	s_nop 1
	v_addc_co_u32_e32 v103, vcc, 0, v103, vcc
	s_waitcnt vmcnt(56)
	v_cvt_pk_bf16_f32 v104, v104, v196
	v_cvt_pk_bf16_f32 v105, v105, v196
	v_cvt_pk_bf16_f32 v106, v106, v196
	v_cvt_pk_bf16_f32 v107, v107, v196
	v_cvt_pk_bf16_f32 v108, v108, v196
	v_cvt_pk_bf16_f32 v109, v109, v196
	v_cvt_pk_bf16_f32 v110, v110, v196
	v_cvt_pk_bf16_f32 v111, v111, v196
	v_cvt_pk_bf16_f32 v112, v112, v196
	v_cvt_pk_bf16_f32 v113, v113, v196
	v_cvt_pk_bf16_f32 v114, v114, v196
	v_cvt_pk_bf16_f32 v115, v115, v196
	v_cvt_pk_bf16_f32 v116, v116, v196
	v_cvt_pk_bf16_f32 v117, v117, v196
	v_cvt_pk_bf16_f32 v118, v118, v196
	v_cvt_pk_bf16_f32 v119, v119, v196
	global_store_short v[100:101], v104, off
	global_store_short v[100:101], v105, off offset:128
	global_store_short v[100:101], v106, off offset:256
	global_store_short v[100:101], v107, off offset:384
	global_store_short v[100:101], v108, off offset:512
	global_store_short v[100:101], v109, off offset:640
	global_store_short v[100:101], v110, off offset:768
	global_store_short v[100:101], v111, off offset:896
	global_store_short v[102:103], v112, off
	global_store_short v[102:103], v113, off offset:128
	global_store_short v[102:103], v114, off offset:256
	global_store_short v[102:103], v115, off offset:384
	global_store_short v[102:103], v116, off offset:512
	global_store_short v[102:103], v117, off offset:640
	global_store_short v[102:103], v118, off offset:768
	global_store_short v[102:103], v119, off offset:896
	v_add_co_u32_e32 v100, vcc, 0x2000, v100
	s_nop 1
	v_addc_co_u32_e32 v101, vcc, 0, v101, vcc
	v_add_co_u32_e32 v102, vcc, 0x2000, v102
	s_nop 1
	v_addc_co_u32_e32 v103, vcc, 0, v103, vcc
	v_cvt_pk_bf16_f32 v120, v120, v196
	v_cvt_pk_bf16_f32 v121, v121, v196
	v_cvt_pk_bf16_f32 v122, v122, v196
	v_cvt_pk_bf16_f32 v123, v123, v196
	v_cvt_pk_bf16_f32 v124, v124, v196
	v_cvt_pk_bf16_f32 v125, v125, v196
	v_cvt_pk_bf16_f32 v126, v126, v196
	v_cvt_pk_bf16_f32 v127, v127, v196
	v_cvt_pk_bf16_f32 v128, v128, v196
	v_cvt_pk_bf16_f32 v129, v129, v196
	v_cvt_pk_bf16_f32 v130, v130, v196
	v_cvt_pk_bf16_f32 v131, v131, v196
	v_cvt_pk_bf16_f32 v132, v132, v196
	v_cvt_pk_bf16_f32 v133, v133, v196
	v_cvt_pk_bf16_f32 v134, v134, v196
	v_cvt_pk_bf16_f32 v135, v135, v196
	global_store_short v[100:101], v120, off
	global_store_short v[100:101], v121, off offset:128
	global_store_short v[100:101], v122, off offset:256
	global_store_short v[100:101], v123, off offset:384
	global_store_short v[100:101], v124, off offset:512
	global_store_short v[100:101], v125, off offset:640
	global_store_short v[100:101], v126, off offset:768
	global_store_short v[100:101], v127, off offset:896
	global_store_short v[102:103], v128, off
	global_store_short v[102:103], v129, off offset:128
	global_store_short v[102:103], v130, off offset:256
	global_store_short v[102:103], v131, off offset:384
	global_store_short v[102:103], v132, off offset:512
	global_store_short v[102:103], v133, off offset:640
	global_store_short v[102:103], v134, off offset:768
	global_store_short v[102:103], v135, off offset:896

.LBB0_434:
	s_and_b32 s16, s2, 1
	s_lshl_b32 s17, s16, 9
	v_readlane_b32 s54, v254, 62
	v_readlane_b32 s55, v254, 63
	v_readlane_b32 s56, v255, 0
	v_readlane_b32 s57, v255, 1
	v_add_lshl_u32 v84, v38, s17, 2
	s_mov_b64 s[62:63], s[54:55]
	global_load_dword v86, v84, s[62:63]
	s_add_u32 s62, s62, 0x1000
	s_addc_u32 s63, s63, 0
	global_load_dword v87, v84, s[62:63]
	s_add_u32 s62, s62, 0x1000
	s_addc_u32 s63, s63, 0
	global_load_dword v88, v84, s[62:63]
	s_add_u32 s62, s62, 0x1000
	s_addc_u32 s63, s63, 0
	global_load_dword v89, v84, s[62:63]
	s_add_u32 s62, s62, 0x1000
	s_addc_u32 s63, s63, 0
	global_load_dword v90, v84, s[62:63]
	s_add_u32 s62, s62, 0x1000
	s_addc_u32 s63, s63, 0
	global_load_dword v91, v84, s[62:63]
	s_add_u32 s62, s62, 0x1000
	s_addc_u32 s63, s63, 0
	global_load_dword v92, v84, s[62:63]
	s_add_u32 s62, s62, 0x1000
	s_addc_u32 s63, s63, 0
	global_load_dword v93, v84, s[62:63]
	v_readfirstlane_b32 s14, v53
	s_lshl_b32 s0, s2, 5
	s_andn2_b32 s0, s0, 63
	s_add_i32 s14, s14, s17
	s_mul_i32 s14, s14, 0x6000
	s_lshl_b32 s1, s0, 2
	s_add_u32 s14, s14, s1
	s_add_u32 s60, s56, s14
	s_addc_u32 s61, s57, 0
	v_lshlrev_b32_e32 v85, 2, v52
	global_load_dword v96, v85, s[60:61]
	s_add_u32 s60, s60, 0x6000
	s_addc_u32 s61, s61, 0
	global_load_dword v97, v85, s[60:61]
	s_add_u32 s60, s60, 0x6000
	s_addc_u32 s61, s61, 0
	global_load_dword v98, v85, s[60:61]
	s_add_u32 s60, s60, 0x6000
	s_addc_u32 s61, s61, 0
	global_load_dword v99, v85, s[60:61]
	s_add_u32 s60, s60, 0x6000
	s_addc_u32 s61, s61, 0
	global_load_dword v100, v85, s[60:61]
	s_add_u32 s60, s60, 0x6000
	s_addc_u32 s61, s61, 0
	global_load_dword v101, v85, s[60:61]
	s_add_u32 s60, s60, 0x6000
	s_addc_u32 s61, s61, 0
	global_load_dword v102, v85, s[60:61]
	s_add_u32 s60, s60, 0x6000
	s_addc_u32 s61, s61, 0
	global_load_dword v103, v85, s[60:61]
	s_add_u32 s60, s60, 0x6000
	s_addc_u32 s61, s61, 0
	global_load_dword v104, v85, s[60:61]
	s_add_u32 s60, s60, 0x6000
	s_addc_u32 s61, s61, 0
	global_load_dword v105, v85, s[60:61]
	s_add_u32 s60, s60, 0x6000
	s_addc_u32 s61, s61, 0
	global_load_dword v106, v85, s[60:61]
	s_add_u32 s60, s60, 0x6000
	s_addc_u32 s61, s61, 0
	global_load_dword v107, v85, s[60:61]
	s_add_u32 s60, s60, 0x6000
	s_addc_u32 s61, s61, 0
	global_load_dword v108, v85, s[60:61]
	s_add_u32 s60, s60, 0x6000
	s_addc_u32 s61, s61, 0
	global_load_dword v109, v85, s[60:61]
	s_add_u32 s60, s60, 0x6000
	s_addc_u32 s61, s61, 0
	global_load_dword v110, v85, s[60:61]
	s_add_u32 s60, s60, 0x6000
	s_addc_u32 s61, s61, 0
	global_load_dword v111, v85, s[60:61]
	s_add_u32 s60, s60, 0x6000
	s_addc_u32 s61, s61, 0
	global_load_dword v112, v85, s[60:61]
	s_add_u32 s60, s60, 0x6000
	s_addc_u32 s61, s61, 0
	global_load_dword v113, v85, s[60:61]
	s_add_u32 s60, s60, 0x6000
	s_addc_u32 s61, s61, 0
	global_load_dword v114, v85, s[60:61]
	s_add_u32 s60, s60, 0x6000
	s_addc_u32 s61, s61, 0
	global_load_dword v115, v85, s[60:61]
	s_add_u32 s60, s60, 0x6000
	s_addc_u32 s61, s61, 0
	global_load_dword v116, v85, s[60:61]
	s_add_u32 s60, s60, 0x6000
	s_addc_u32 s61, s61, 0
	global_load_dword v117, v85, s[60:61]
	s_add_u32 s60, s60, 0x6000
	s_addc_u32 s61, s61, 0
	global_load_dword v118, v85, s[60:61]
	s_add_u32 s60, s60, 0x6000
	s_addc_u32 s61, s61, 0
	global_load_dword v119, v85, s[60:61]
	s_add_u32 s60, s60, 0x6000
	s_addc_u32 s61, s61, 0
	global_load_dword v120, v85, s[60:61]
	s_add_u32 s60, s60, 0x6000
	s_addc_u32 s61, s61, 0
	global_load_dword v121, v85, s[60:61]
	s_add_u32 s60, s60, 0x6000
	s_addc_u32 s61, s61, 0
	global_load_dword v122, v85, s[60:61]
	s_add_u32 s60, s60, 0x6000
	s_addc_u32 s61, s61, 0
	global_load_dword v123, v85, s[60:61]
	s_add_u32 s60, s60, 0x6000
	s_addc_u32 s61, s61, 0
	global_load_dword v124, v85, s[60:61]
	s_add_u32 s60, s60, 0x6000
	s_addc_u32 s61, s61, 0
	global_load_dword v125, v85, s[60:61]
	s_add_u32 s60, s60, 0x6000
	s_addc_u32 s61, s61, 0
	global_load_dword v126, v85, s[60:61]
	s_add_u32 s60, s60, 0x6000
	s_addc_u32 s61, s61, 0
	global_load_dword v127, v85, s[60:61]
	s_add_u32 s60, s60, 0x6000
	s_addc_u32 s61, s61, 0
	global_load_dword v128, v85, s[60:61]
	s_add_u32 s60, s60, 0x6000
	s_addc_u32 s61, s61, 0
	global_load_dword v129, v85, s[60:61]
	s_add_u32 s60, s60, 0x6000
	s_addc_u32 s61, s61, 0
	global_load_dword v130, v85, s[60:61]
	s_add_u32 s60, s60, 0x6000
	s_addc_u32 s61, s61, 0
	global_load_dword v131, v85, s[60:61]
	s_add_u32 s60, s60, 0x6000
	s_addc_u32 s61, s61, 0
	global_load_dword v132, v85, s[60:61]
	s_add_u32 s60, s60, 0x6000
	s_addc_u32 s61, s61, 0
	global_load_dword v133, v85, s[60:61]
	s_add_u32 s60, s60, 0x6000
	s_addc_u32 s61, s61, 0
	global_load_dword v134, v85, s[60:61]
	s_add_u32 s60, s60, 0x6000
	s_addc_u32 s61, s61, 0
	global_load_dword v135, v85, s[60:61]
	s_add_u32 s60, s60, 0x6000
	s_addc_u32 s61, s61, 0
	global_load_dword v136, v85, s[60:61]
	s_add_u32 s60, s60, 0x6000
	s_addc_u32 s61, s61, 0
	global_load_dword v137, v85, s[60:61]
	s_add_u32 s60, s60, 0x6000
	s_addc_u32 s61, s61, 0
	global_load_dword v138, v85, s[60:61]
	s_add_u32 s60, s60, 0x6000
	s_addc_u32 s61, s61, 0
	global_load_dword v139, v85, s[60:61]
	s_add_u32 s60, s60, 0x6000
	s_addc_u32 s61, s61, 0
	global_load_dword v140, v85, s[60:61]
	s_add_u32 s60, s60, 0x6000
	s_addc_u32 s61, s61, 0
	global_load_dword v141, v85, s[60:61]
	s_add_u32 s60, s60, 0x6000
	s_addc_u32 s61, s61, 0
	global_load_dword v142, v85, s[60:61]
	s_add_u32 s60, s60, 0x6000
	s_addc_u32 s61, s61, 0
	global_load_dword v143, v85, s[60:61]
	s_add_u32 s60, s60, 0x6000
	s_addc_u32 s61, s61, 0
	v_or_b32_e32 v46, s0, v52
	v_ashrrev_i32_e32 v47, 31, v46
	v_mov_b32_e32 v14, 0
	v_mov_b32_e32 v15, 0
	v_mov_b32_e32 v16, 0
	v_mov_b32_e32 v17, 0
	v_mov_b32_e32 v18, 0
	v_mov_b32_e32 v19, 0
	v_mov_b32_e32 v20, 0
	v_mov_b32_e32 v21, 0
	s_waitcnt vmcnt(48)
	v_mul_f32_e32 v2, 0xbfb8aa3b, v86
	v_mul_f32_e32 v3, 0xbfb8aa3b, v87
	v_mul_f32_e32 v4, 0xbfb8aa3b, v88
	v_mul_f32_e32 v5, 0xbfb8aa3b, v89
	v_mul_f32_e32 v6, 0xbfb8aa3b, v90
	v_mul_f32_e32 v7, 0xbfb8aa3b, v91
	v_mul_f32_e32 v8, 0xbfb8aa3b, v92
	v_mul_f32_e32 v9, 0xbfb8aa3b, v93
	v_exp_f32_e32 v2, v2
	v_exp_f32_e32 v3, v3
	v_exp_f32_e32 v4, v4
	v_exp_f32_e32 v5, v5
	v_exp_f32_e32 v6, v6
	v_exp_f32_e32 v7, v7
	v_exp_f32_e32 v8, v8
	v_exp_f32_e32 v9, v9
	v_add_f32_e32 v2, 1.0, v2
	v_add_f32_e32 v3, 1.0, v3
	v_add_f32_e32 v4, 1.0, v4
	v_add_f32_e32 v5, 1.0, v5
	v_add_f32_e32 v6, 1.0, v6
	v_add_f32_e32 v7, 1.0, v7
	v_add_f32_e32 v8, 1.0, v8
	v_add_f32_e32 v9, 1.0, v9
	v_rcp_f32_e32 v2, v2
	v_rcp_f32_e32 v3, v3
	v_rcp_f32_e32 v4, v4
	v_rcp_f32_e32 v5, v5
	v_rcp_f32_e32 v6, v6
	v_rcp_f32_e32 v7, v7
	v_rcp_f32_e32 v8, v8
	v_rcp_f32_e32 v9, v9
	v_mul_f32_e32 v86, v86, v2
	v_mul_f32_e32 v87, v87, v3
	v_mul_f32_e32 v88, v88, v4
	v_mul_f32_e32 v89, v89, v5
	v_mul_f32_e32 v90, v90, v6
	v_mul_f32_e32 v91, v91, v7
	v_mul_f32_e32 v92, v92, v8
	v_mul_f32_e32 v93, v93, v9
	ds_write_b32 v59, v86
	ds_write_b32 v59, v87 offset:2048
	ds_write_b32 v59, v88 offset:4096
	ds_write_b32 v59, v89 offset:6144
	ds_write_b32 v59, v90 offset:8192
	ds_write_b32 v59, v91 offset:10240
	ds_write_b32 v59, v92 offset:12288
	ds_write_b32 v59, v93 offset:14336
	s_waitcnt lgkmcnt(0)
	s_barrier
	ds_read_b128 v[64:67], v54
	ds_read_b128 v[68:71], v54 offset:2048
	ds_read_b128 v[72:75], v54 offset:4096
	ds_read_b128 v[76:79], v54 offset:6144
	ds_read_b128 v[80:83], v54 offset:8192
	ds_read_b128 v[2:5], v54 offset:10240
	ds_read_b128 v[6:9], v54 offset:12288
	ds_read_b128 v[10:13], v54 offset:14336
	s_waitcnt vmcnt(32)
	global_load_dword v144, v85, s[60:61]
	s_add_u32 s60, s60, 0x6000
	s_addc_u32 s61, s61, 0
	global_load_dword v145, v85, s[60:61]
	s_add_u32 s60, s60, 0x6000
	s_addc_u32 s61, s61, 0
	global_load_dword v146, v85, s[60:61]
	s_add_u32 s60, s60, 0x6000
	s_addc_u32 s61, s61, 0
	global_load_dword v147, v85, s[60:61]
	s_add_u32 s60, s60, 0x6000
	s_addc_u32 s61, s61, 0
	global_load_dword v148, v85, s[60:61]
	s_add_u32 s60, s60, 0x6000
	s_addc_u32 s61, s61, 0
	global_load_dword v149, v85, s[60:61]
	s_add_u32 s60, s60, 0x6000
	s_addc_u32 s61, s61, 0
	global_load_dword v150, v85, s[60:61]
	s_add_u32 s60, s60, 0x6000
	s_addc_u32 s61, s61, 0
	global_load_dword v151, v85, s[60:61]
	s_add_u32 s60, s60, 0x6000
	s_addc_u32 s61, s61, 0
	global_load_dword v152, v85, s[60:61]
	s_add_u32 s60, s60, 0x6000
	s_addc_u32 s61, s61, 0
	global_load_dword v153, v85, s[60:61]
	s_add_u32 s60, s60, 0x6000
	s_addc_u32 s61, s61, 0
	global_load_dword v154, v85, s[60:61]
	s_add_u32 s60, s60, 0x6000
	s_addc_u32 s61, s61, 0
	global_load_dword v155, v85, s[60:61]
	s_add_u32 s60, s60, 0x6000
	s_addc_u32 s61, s61, 0
	global_load_dword v156, v85, s[60:61]
	s_add_u32 s60, s60, 0x6000
	s_addc_u32 s61, s61, 0
	global_load_dword v157, v85, s[60:61]
	s_add_u32 s60, s60, 0x6000
	s_addc_u32 s61, s61, 0
	global_load_dword v158, v85, s[60:61]
	s_add_u32 s60, s60, 0x6000
	s_addc_u32 s61, s61, 0
	global_load_dword v159, v85, s[60:61]
	ds_read_b128 v[160:163], v54 offset:16
	ds_read_b128 v[164:167], v54 offset:2064
	ds_read_b128 v[168:171], v54 offset:4112
	ds_read_b128 v[172:175], v54 offset:6160
	s_waitcnt lgkmcnt(8)
	v_fmac_f32_e32 v20, v96, v64
	v_fmac_f32_e32 v21, v96, v68
	v_fmac_f32_e32 v18, v96, v72
	v_fmac_f32_e32 v19, v96, v76
	v_fmac_f32_e32 v20, v97, v65
	v_fmac_f32_e32 v21, v97, v69
	v_fmac_f32_e32 v18, v97, v73
	v_fmac_f32_e32 v19, v97, v77
	v_fmac_f32_e32 v20, v98, v66
	v_fmac_f32_e32 v21, v98, v70
	v_fmac_f32_e32 v18, v98, v74
	v_fmac_f32_e32 v19, v98, v78
	v_fmac_f32_e32 v20, v99, v67
	v_fmac_f32_e32 v21, v99, v71
	v_fmac_f32_e32 v18, v99, v75
	v_fmac_f32_e32 v19, v99, v79
	ds_read_b128 v[64:67], v54 offset:8208
	ds_read_b128 v[68:71], v54 offset:10256
	ds_read_b128 v[72:75], v54 offset:12304
	ds_read_b128 v[76:79], v54 offset:14352
	s_waitcnt lgkmcnt(8)
	v_fmac_f32_e32 v16, v96, v80
	v_fmac_f32_e32 v17, v96, v2
	v_fmac_f32_e32 v14, v96, v6
	v_fmac_f32_e32 v15, v96, v10
	v_fmac_f32_e32 v16, v97, v81
	v_fmac_f32_e32 v17, v97, v3
	v_fmac_f32_e32 v14, v97, v7
	v_fmac_f32_e32 v15, v97, v11
	v_fmac_f32_e32 v16, v98, v82
	v_fmac_f32_e32 v17, v98, v4
	v_fmac_f32_e32 v14, v98, v8
	v_fmac_f32_e32 v15, v98, v12
	v_fmac_f32_e32 v16, v99, v83
	v_fmac_f32_e32 v17, v99, v5
	v_fmac_f32_e32 v14, v99, v9
	v_fmac_f32_e32 v15, v99, v13
	ds_read_b128 v[80:83], v54 offset:32
	ds_read_b128 v[2:5], v54 offset:2080
	ds_read_b128 v[6:9], v54 offset:4128
	ds_read_b128 v[10:13], v54 offset:6176
	s_waitcnt lgkmcnt(8)
	v_fmac_f32_e32 v20, v100, v160
	v_fmac_f32_e32 v21, v100, v164
	v_fmac_f32_e32 v18, v100, v168
	v_fmac_f32_e32 v19, v100, v172
	v_fmac_f32_e32 v20, v101, v161
	v_fmac_f32_e32 v21, v101, v165
	v_fmac_f32_e32 v18, v101, v169
	v_fmac_f32_e32 v19, v101, v173
	v_fmac_f32_e32 v20, v102, v162
	v_fmac_f32_e32 v21, v102, v166
	v_fmac_f32_e32 v18, v102, v170
	v_fmac_f32_e32 v19, v102, v174
	v_fmac_f32_e32 v20, v103, v163
	v_fmac_f32_e32 v21, v103, v167
	v_fmac_f32_e32 v18, v103, v171
	v_fmac_f32_e32 v19, v103, v175
	ds_read_b128 v[160:163], v54 offset:8224
	ds_read_b128 v[164:167], v54 offset:10272
	ds_read_b128 v[168:171], v54 offset:12320
	ds_read_b128 v[172:175], v54 offset:14368
	s_waitcnt lgkmcnt(8)
	v_fmac_f32_e32 v16, v100, v64
	v_fmac_f32_e32 v17, v100, v68
	v_fmac_f32_e32 v14, v100, v72
	v_fmac_f32_e32 v15, v100, v76
	v_fmac_f32_e32 v16, v101, v65
	v_fmac_f32_e32 v17, v101, v69
	v_fmac_f32_e32 v14, v101, v73
	v_fmac_f32_e32 v15, v101, v77
	v_fmac_f32_e32 v16, v102, v66
	v_fmac_f32_e32 v17, v102, v70
	v_fmac_f32_e32 v14, v102, v74
	v_fmac_f32_e32 v15, v102, v78
	v_fmac_f32_e32 v16, v103, v67
	v_fmac_f32_e32 v17, v103, v71
	v_fmac_f32_e32 v14, v103, v75
	v_fmac_f32_e32 v15, v103, v79
	ds_read_b128 v[64:67], v54 offset:48
	ds_read_b128 v[68:71], v54 offset:2096
	ds_read_b128 v[72:75], v54 offset:4144
	ds_read_b128 v[76:79], v54 offset:6192
	s_waitcnt lgkmcnt(8)
	v_fmac_f32_e32 v20, v104, v80
	v_fmac_f32_e32 v21, v104, v2
	v_fmac_f32_e32 v18, v104, v6
	v_fmac_f32_e32 v19, v104, v10
	v_fmac_f32_e32 v20, v105, v81
	v_fmac_f32_e32 v21, v105, v3
	v_fmac_f32_e32 v18, v105, v7
	v_fmac_f32_e32 v19, v105, v11
	v_fmac_f32_e32 v20, v106, v82
	v_fmac_f32_e32 v21, v106, v4
	v_fmac_f32_e32 v18, v106, v8
	v_fmac_f32_e32 v19, v106, v12
	v_fmac_f32_e32 v20, v107, v83
	v_fmac_f32_e32 v21, v107, v5
	v_fmac_f32_e32 v18, v107, v9
	v_fmac_f32_e32 v19, v107, v13
	ds_read_b128 v[80:83], v54 offset:8240
	ds_read_b128 v[2:5], v54 offset:10288
	ds_read_b128 v[6:9], v54 offset:12336
	ds_read_b128 v[10:13], v54 offset:14384
	s_waitcnt lgkmcnt(8)
	v_fmac_f32_e32 v16, v104, v160
	v_fmac_f32_e32 v17, v104, v164
	v_fmac_f32_e32 v14, v104, v168
	v_fmac_f32_e32 v15, v104, v172
	v_fmac_f32_e32 v16, v105, v161
	v_fmac_f32_e32 v17, v105, v165
	v_fmac_f32_e32 v14, v105, v169
	v_fmac_f32_e32 v15, v105, v173
	v_fmac_f32_e32 v16, v106, v162
	v_fmac_f32_e32 v17, v106, v166
	v_fmac_f32_e32 v14, v106, v170
	v_fmac_f32_e32 v15, v106, v174
	v_fmac_f32_e32 v16, v107, v163
	v_fmac_f32_e32 v17, v107, v167
	v_fmac_f32_e32 v14, v107, v171
	v_fmac_f32_e32 v15, v107, v175
	ds_read_b128 v[160:163], v54 offset:64
	ds_read_b128 v[164:167], v54 offset:2112
	ds_read_b128 v[168:171], v54 offset:4160
	ds_read_b128 v[172:175], v54 offset:6208
	s_waitcnt lgkmcnt(8)
	v_fmac_f32_e32 v20, v108, v64
	v_fmac_f32_e32 v21, v108, v68
	v_fmac_f32_e32 v18, v108, v72
	v_fmac_f32_e32 v19, v108, v76
	v_fmac_f32_e32 v20, v109, v65
	v_fmac_f32_e32 v21, v109, v69
	v_fmac_f32_e32 v18, v109, v73
	v_fmac_f32_e32 v19, v109, v77
	v_fmac_f32_e32 v20, v110, v66
	v_fmac_f32_e32 v21, v110, v70
	v_fmac_f32_e32 v18, v110, v74
	v_fmac_f32_e32 v19, v110, v78
	v_fmac_f32_e32 v20, v111, v67
	v_fmac_f32_e32 v21, v111, v71
	v_fmac_f32_e32 v18, v111, v75
	v_fmac_f32_e32 v19, v111, v79
	ds_read_b128 v[64:67], v54 offset:8256
	ds_read_b128 v[68:71], v54 offset:10304
	ds_read_b128 v[72:75], v54 offset:12352
	ds_read_b128 v[76:79], v54 offset:14400
	s_waitcnt lgkmcnt(8)
	v_fmac_f32_e32 v16, v108, v80
	v_fmac_f32_e32 v17, v108, v2
	v_fmac_f32_e32 v14, v108, v6
	v_fmac_f32_e32 v15, v108, v10
	v_fmac_f32_e32 v16, v109, v81
	v_fmac_f32_e32 v17, v109, v3
	v_fmac_f32_e32 v14, v109, v7
	v_fmac_f32_e32 v15, v109, v11
	v_fmac_f32_e32 v16, v110, v82
	v_fmac_f32_e32 v17, v110, v4
	v_fmac_f32_e32 v14, v110, v8
	v_fmac_f32_e32 v15, v110, v12
	v_fmac_f32_e32 v16, v111, v83
	v_fmac_f32_e32 v17, v111, v5
	v_fmac_f32_e32 v14, v111, v9
	v_fmac_f32_e32 v15, v111, v13
	s_waitcnt vmcnt(32)
	ds_read_b128 v[80:83], v54 offset:80
	ds_read_b128 v[2:5], v54 offset:2128
	ds_read_b128 v[6:9], v54 offset:4176
	ds_read_b128 v[10:13], v54 offset:6224
	s_waitcnt lgkmcnt(8)
	v_fmac_f32_e32 v20, v112, v160
	v_fmac_f32_e32 v21, v112, v164
	v_fmac_f32_e32 v18, v112, v168
	v_fmac_f32_e32 v19, v112, v172
	v_fmac_f32_e32 v20, v113, v161
	v_fmac_f32_e32 v21, v113, v165
	v_fmac_f32_e32 v18, v113, v169
	v_fmac_f32_e32 v19, v113, v173
	v_fmac_f32_e32 v20, v114, v162
	v_fmac_f32_e32 v21, v114, v166
	v_fmac_f32_e32 v18, v114, v170
	v_fmac_f32_e32 v19, v114, v174
	v_fmac_f32_e32 v20, v115, v163
	v_fmac_f32_e32 v21, v115, v167
	v_fmac_f32_e32 v18, v115, v171
	v_fmac_f32_e32 v19, v115, v175
	ds_read_b128 v[160:163], v54 offset:8272
	ds_read_b128 v[164:167], v54 offset:10320
	ds_read_b128 v[168:171], v54 offset:12368
	ds_read_b128 v[172:175], v54 offset:14416
	s_waitcnt lgkmcnt(8)
	v_fmac_f32_e32 v16, v112, v64
	v_fmac_f32_e32 v17, v112, v68
	v_fmac_f32_e32 v14, v112, v72
	v_fmac_f32_e32 v15, v112, v76
	v_fmac_f32_e32 v16, v113, v65
	v_fmac_f32_e32 v17, v113, v69
	v_fmac_f32_e32 v14, v113, v73
	v_fmac_f32_e32 v15, v113, v77
	v_fmac_f32_e32 v16, v114, v66
	v_fmac_f32_e32 v17, v114, v70
	v_fmac_f32_e32 v14, v114, v74
	v_fmac_f32_e32 v15, v114, v78
	v_fmac_f32_e32 v16, v115, v67
	v_fmac_f32_e32 v17, v115, v71
	v_fmac_f32_e32 v14, v115, v75
	v_fmac_f32_e32 v15, v115, v79
	ds_read_b128 v[64:67], v54 offset:96
	ds_read_b128 v[68:71], v54 offset:2144
	ds_read_b128 v[72:75], v54 offset:4192
	ds_read_b128 v[76:79], v54 offset:6240
	s_waitcnt lgkmcnt(8)
	v_fmac_f32_e32 v20, v116, v80
	v_fmac_f32_e32 v21, v116, v2
	v_fmac_f32_e32 v18, v116, v6
	v_fmac_f32_e32 v19, v116, v10
	v_fmac_f32_e32 v20, v117, v81
	v_fmac_f32_e32 v21, v117, v3
	v_fmac_f32_e32 v18, v117, v7
	v_fmac_f32_e32 v19, v117, v11
	v_fmac_f32_e32 v20, v118, v82
	v_fmac_f32_e32 v21, v118, v4
	v_fmac_f32_e32 v18, v118, v8
	v_fmac_f32_e32 v19, v118, v12
	v_fmac_f32_e32 v20, v119, v83
	v_fmac_f32_e32 v21, v119, v5
	v_fmac_f32_e32 v18, v119, v9
	v_fmac_f32_e32 v19, v119, v13
	ds_read_b128 v[80:83], v54 offset:8288
	ds_read_b128 v[2:5], v54 offset:10336
	ds_read_b128 v[6:9], v54 offset:12384
	ds_read_b128 v[10:13], v54 offset:14432
	s_waitcnt lgkmcnt(8)
	v_fmac_f32_e32 v16, v116, v160
	v_fmac_f32_e32 v17, v116, v164
	v_fmac_f32_e32 v14, v116, v168
	v_fmac_f32_e32 v15, v116, v172
	v_fmac_f32_e32 v16, v117, v161
	v_fmac_f32_e32 v17, v117, v165
	v_fmac_f32_e32 v14, v117, v169
	v_fmac_f32_e32 v15, v117, v173
	v_fmac_f32_e32 v16, v118, v162
	v_fmac_f32_e32 v17, v118, v166
	v_fmac_f32_e32 v14, v118, v170
	v_fmac_f32_e32 v15, v118, v174
	v_fmac_f32_e32 v16, v119, v163
	v_fmac_f32_e32 v17, v119, v167
	v_fmac_f32_e32 v14, v119, v171
	v_fmac_f32_e32 v15, v119, v175
	ds_read_b128 v[160:163], v54 offset:112
	ds_read_b128 v[164:167], v54 offset:2160
	ds_read_b128 v[168:171], v54 offset:4208
	ds_read_b128 v[172:175], v54 offset:6256
	s_waitcnt lgkmcnt(8)
	v_fmac_f32_e32 v20, v120, v64
	v_fmac_f32_e32 v21, v120, v68
	v_fmac_f32_e32 v18, v120, v72
	v_fmac_f32_e32 v19, v120, v76
	v_fmac_f32_e32 v20, v121, v65
	v_fmac_f32_e32 v21, v121, v69
	v_fmac_f32_e32 v18, v121, v73
	v_fmac_f32_e32 v19, v121, v77
	v_fmac_f32_e32 v20, v122, v66
	v_fmac_f32_e32 v21, v122, v70
	v_fmac_f32_e32 v18, v122, v74
	v_fmac_f32_e32 v19, v122, v78
	v_fmac_f32_e32 v20, v123, v67
	v_fmac_f32_e32 v21, v123, v71
	v_fmac_f32_e32 v18, v123, v75
	v_fmac_f32_e32 v19, v123, v79
	ds_read_b128 v[64:67], v54 offset:8304
	ds_read_b128 v[68:71], v54 offset:10352
	ds_read_b128 v[72:75], v54 offset:12400
	ds_read_b128 v[76:79], v54 offset:14448
	s_waitcnt lgkmcnt(8)
	v_fmac_f32_e32 v16, v120, v80
	v_fmac_f32_e32 v17, v120, v2
	v_fmac_f32_e32 v14, v120, v6
	v_fmac_f32_e32 v15, v120, v10
	v_fmac_f32_e32 v16, v121, v81
	v_fmac_f32_e32 v17, v121, v3
	v_fmac_f32_e32 v14, v121, v7
	v_fmac_f32_e32 v15, v121, v11
	v_fmac_f32_e32 v16, v122, v82
	v_fmac_f32_e32 v17, v122, v4
	v_fmac_f32_e32 v14, v122, v8
	v_fmac_f32_e32 v15, v122, v12
	v_fmac_f32_e32 v16, v123, v83
	v_fmac_f32_e32 v17, v123, v5
	v_fmac_f32_e32 v14, v123, v9
	v_fmac_f32_e32 v15, v123, v13
	ds_read_b128 v[80:83], v54 offset:128
	ds_read_b128 v[2:5], v54 offset:2176
	ds_read_b128 v[6:9], v54 offset:4224
	ds_read_b128 v[10:13], v54 offset:6272
	s_waitcnt lgkmcnt(8)
	v_fmac_f32_e32 v20, v124, v160
	v_fmac_f32_e32 v21, v124, v164
	v_fmac_f32_e32 v18, v124, v168
	v_fmac_f32_e32 v19, v124, v172
	v_fmac_f32_e32 v20, v125, v161
	v_fmac_f32_e32 v21, v125, v165
	v_fmac_f32_e32 v18, v125, v169
	v_fmac_f32_e32 v19, v125, v173
	v_fmac_f32_e32 v20, v126, v162
	v_fmac_f32_e32 v21, v126, v166
	v_fmac_f32_e32 v18, v126, v170
	v_fmac_f32_e32 v19, v126, v174
	v_fmac_f32_e32 v20, v127, v163
	v_fmac_f32_e32 v21, v127, v167
	v_fmac_f32_e32 v18, v127, v171
	v_fmac_f32_e32 v19, v127, v175
	ds_read_b128 v[160:163], v54 offset:8320
	ds_read_b128 v[164:167], v54 offset:10368
	ds_read_b128 v[168:171], v54 offset:12416
	ds_read_b128 v[172:175], v54 offset:14464
	s_waitcnt lgkmcnt(8)
	v_fmac_f32_e32 v16, v124, v64
	v_fmac_f32_e32 v17, v124, v68
	v_fmac_f32_e32 v14, v124, v72
	v_fmac_f32_e32 v15, v124, v76
	v_fmac_f32_e32 v16, v125, v65
	v_fmac_f32_e32 v17, v125, v69
	v_fmac_f32_e32 v14, v125, v73
	v_fmac_f32_e32 v15, v125, v77
	v_fmac_f32_e32 v16, v126, v66
	v_fmac_f32_e32 v17, v126, v70
	v_fmac_f32_e32 v14, v126, v74
	v_fmac_f32_e32 v15, v126, v78
	v_fmac_f32_e32 v16, v127, v67
	v_fmac_f32_e32 v17, v127, v71
	v_fmac_f32_e32 v14, v127, v75
	v_fmac_f32_e32 v15, v127, v79
	s_waitcnt vmcnt(16)
	ds_read_b128 v[64:67], v54 offset:144
	ds_read_b128 v[68:71], v54 offset:2192
	ds_read_b128 v[72:75], v54 offset:4240
	ds_read_b128 v[76:79], v54 offset:6288
	s_waitcnt lgkmcnt(8)
	v_fmac_f32_e32 v20, v128, v80
	v_fmac_f32_e32 v21, v128, v2
	v_fmac_f32_e32 v18, v128, v6
	v_fmac_f32_e32 v19, v128, v10
	v_fmac_f32_e32 v20, v129, v81
	v_fmac_f32_e32 v21, v129, v3
	v_fmac_f32_e32 v18, v129, v7
	v_fmac_f32_e32 v19, v129, v11
	v_fmac_f32_e32 v20, v130, v82
	v_fmac_f32_e32 v21, v130, v4
	v_fmac_f32_e32 v18, v130, v8
	v_fmac_f32_e32 v19, v130, v12
	v_fmac_f32_e32 v20, v131, v83
	v_fmac_f32_e32 v21, v131, v5
	v_fmac_f32_e32 v18, v131, v9
	v_fmac_f32_e32 v19, v131, v13
	ds_read_b128 v[80:83], v54 offset:8336
	ds_read_b128 v[2:5], v54 offset:10384
	ds_read_b128 v[6:9], v54 offset:12432
	ds_read_b128 v[10:13], v54 offset:14480
	s_waitcnt lgkmcnt(8)
	v_fmac_f32_e32 v16, v128, v160
	v_fmac_f32_e32 v17, v128, v164
	v_fmac_f32_e32 v14, v128, v168
	v_fmac_f32_e32 v15, v128, v172
	v_fmac_f32_e32 v16, v129, v161
	v_fmac_f32_e32 v17, v129, v165
	v_fmac_f32_e32 v14, v129, v169
	v_fmac_f32_e32 v15, v129, v173
	v_fmac_f32_e32 v16, v130, v162
	v_fmac_f32_e32 v17, v130, v166
	v_fmac_f32_e32 v14, v130, v170
	v_fmac_f32_e32 v15, v130, v174
	v_fmac_f32_e32 v16, v131, v163
	v_fmac_f32_e32 v17, v131, v167
	v_fmac_f32_e32 v14, v131, v171
	v_fmac_f32_e32 v15, v131, v175
	ds_read_b128 v[160:163], v54 offset:160
	ds_read_b128 v[164:167], v54 offset:2208
	ds_read_b128 v[168:171], v54 offset:4256
	ds_read_b128 v[172:175], v54 offset:6304
	s_waitcnt lgkmcnt(8)
	v_fmac_f32_e32 v20, v132, v64
	v_fmac_f32_e32 v21, v132, v68
	v_fmac_f32_e32 v18, v132, v72
	v_fmac_f32_e32 v19, v132, v76
	v_fmac_f32_e32 v20, v133, v65
	v_fmac_f32_e32 v21, v133, v69
	v_fmac_f32_e32 v18, v133, v73
	v_fmac_f32_e32 v19, v133, v77
	v_fmac_f32_e32 v20, v134, v66
	v_fmac_f32_e32 v21, v134, v70
	v_fmac_f32_e32 v18, v134, v74
	v_fmac_f32_e32 v19, v134, v78
	v_fmac_f32_e32 v20, v135, v67
	v_fmac_f32_e32 v21, v135, v71
	v_fmac_f32_e32 v18, v135, v75
	v_fmac_f32_e32 v19, v135, v79
	ds_read_b128 v[64:67], v54 offset:8352
	ds_read_b128 v[68:71], v54 offset:10400
	ds_read_b128 v[72:75], v54 offset:12448
	ds_read_b128 v[76:79], v54 offset:14496
	s_waitcnt lgkmcnt(8)
	v_fmac_f32_e32 v16, v132, v80
	v_fmac_f32_e32 v17, v132, v2
	v_fmac_f32_e32 v14, v132, v6
	v_fmac_f32_e32 v15, v132, v10
	v_fmac_f32_e32 v16, v133, v81
	v_fmac_f32_e32 v17, v133, v3
	v_fmac_f32_e32 v14, v133, v7
	v_fmac_f32_e32 v15, v133, v11
	v_fmac_f32_e32 v16, v134, v82
	v_fmac_f32_e32 v17, v134, v4
	v_fmac_f32_e32 v14, v134, v8
	v_fmac_f32_e32 v15, v134, v12
	v_fmac_f32_e32 v16, v135, v83
	v_fmac_f32_e32 v17, v135, v5
	v_fmac_f32_e32 v14, v135, v9
	v_fmac_f32_e32 v15, v135, v13
	ds_read_b128 v[80:83], v54 offset:176
	ds_read_b128 v[2:5], v54 offset:2224
	ds_read_b128 v[6:9], v54 offset:4272
	ds_read_b128 v[10:13], v54 offset:6320
	s_waitcnt lgkmcnt(8)
	v_fmac_f32_e32 v20, v136, v160
	v_fmac_f32_e32 v21, v136, v164
	v_fmac_f32_e32 v18, v136, v168
	v_fmac_f32_e32 v19, v136, v172
	v_fmac_f32_e32 v20, v137, v161
	v_fmac_f32_e32 v21, v137, v165
	v_fmac_f32_e32 v18, v137, v169
	v_fmac_f32_e32 v19, v137, v173
	v_fmac_f32_e32 v20, v138, v162
	v_fmac_f32_e32 v21, v138, v166
	v_fmac_f32_e32 v18, v138, v170
	v_fmac_f32_e32 v19, v138, v174
	v_fmac_f32_e32 v20, v139, v163
	v_fmac_f32_e32 v21, v139, v167
	v_fmac_f32_e32 v18, v139, v171
	v_fmac_f32_e32 v19, v139, v175
	ds_read_b128 v[160:163], v54 offset:8368
	ds_read_b128 v[164:167], v54 offset:10416
	ds_read_b128 v[168:171], v54 offset:12464
	ds_read_b128 v[172:175], v54 offset:14512
	s_waitcnt lgkmcnt(8)
	v_fmac_f32_e32 v16, v136, v64
	v_fmac_f32_e32 v17, v136, v68
	v_fmac_f32_e32 v14, v136, v72
	v_fmac_f32_e32 v15, v136, v76
	v_fmac_f32_e32 v16, v137, v65
	v_fmac_f32_e32 v17, v137, v69
	v_fmac_f32_e32 v14, v137, v73
	v_fmac_f32_e32 v15, v137, v77
	v_fmac_f32_e32 v16, v138, v66
	v_fmac_f32_e32 v17, v138, v70
	v_fmac_f32_e32 v14, v138, v74
	v_fmac_f32_e32 v15, v138, v78
	v_fmac_f32_e32 v16, v139, v67
	v_fmac_f32_e32 v17, v139, v71
	v_fmac_f32_e32 v14, v139, v75
	v_fmac_f32_e32 v15, v139, v79
	ds_read_b128 v[64:67], v54 offset:192
	ds_read_b128 v[68:71], v54 offset:2240
	ds_read_b128 v[72:75], v54 offset:4288
	ds_read_b128 v[76:79], v54 offset:6336
	s_waitcnt lgkmcnt(8)
	v_fmac_f32_e32 v20, v140, v80
	v_fmac_f32_e32 v21, v140, v2
	v_fmac_f32_e32 v18, v140, v6
	v_fmac_f32_e32 v19, v140, v10
	v_fmac_f32_e32 v20, v141, v81
	v_fmac_f32_e32 v21, v141, v3
	v_fmac_f32_e32 v18, v141, v7
	v_fmac_f32_e32 v19, v141, v11
	v_fmac_f32_e32 v20, v142, v82
	v_fmac_f32_e32 v21, v142, v4
	v_fmac_f32_e32 v18, v142, v8
	v_fmac_f32_e32 v19, v142, v12
	v_fmac_f32_e32 v20, v143, v83
	v_fmac_f32_e32 v21, v143, v5
	v_fmac_f32_e32 v18, v143, v9
	v_fmac_f32_e32 v19, v143, v13
	ds_read_b128 v[80:83], v54 offset:8384
	ds_read_b128 v[2:5], v54 offset:10432
	ds_read_b128 v[6:9], v54 offset:12480
	ds_read_b128 v[10:13], v54 offset:14528
	s_waitcnt lgkmcnt(8)
	v_fmac_f32_e32 v16, v140, v160
	v_fmac_f32_e32 v17, v140, v164
	v_fmac_f32_e32 v14, v140, v168
	v_fmac_f32_e32 v15, v140, v172
	v_fmac_f32_e32 v16, v141, v161
	v_fmac_f32_e32 v17, v141, v165
	v_fmac_f32_e32 v14, v141, v169
	v_fmac_f32_e32 v15, v141, v173
	v_fmac_f32_e32 v16, v142, v162
	v_fmac_f32_e32 v17, v142, v166
	v_fmac_f32_e32 v14, v142, v170
	v_fmac_f32_e32 v15, v142, v174
	v_fmac_f32_e32 v16, v143, v163
	v_fmac_f32_e32 v17, v143, v167
	v_fmac_f32_e32 v14, v143, v171
	v_fmac_f32_e32 v15, v143, v175
	s_waitcnt vmcnt(0)
	ds_read_b128 v[160:163], v54 offset:208
	ds_read_b128 v[164:167], v54 offset:2256
	ds_read_b128 v[168:171], v54 offset:4304
	ds_read_b128 v[172:175], v54 offset:6352
	s_waitcnt lgkmcnt(8)
	v_fmac_f32_e32 v20, v144, v64
	v_fmac_f32_e32 v21, v144, v68
	v_fmac_f32_e32 v18, v144, v72
	v_fmac_f32_e32 v19, v144, v76
	v_fmac_f32_e32 v20, v145, v65
	v_fmac_f32_e32 v21, v145, v69
	v_fmac_f32_e32 v18, v145, v73
	v_fmac_f32_e32 v19, v145, v77
	v_fmac_f32_e32 v20, v146, v66
	v_fmac_f32_e32 v21, v146, v70
	v_fmac_f32_e32 v18, v146, v74
	v_fmac_f32_e32 v19, v146, v78
	v_fmac_f32_e32 v20, v147, v67
	v_fmac_f32_e32 v21, v147, v71
	v_fmac_f32_e32 v18, v147, v75
	v_fmac_f32_e32 v19, v147, v79
	ds_read_b128 v[64:67], v54 offset:8400
	ds_read_b128 v[68:71], v54 offset:10448
	ds_read_b128 v[72:75], v54 offset:12496
	ds_read_b128 v[76:79], v54 offset:14544
	s_waitcnt lgkmcnt(8)
	v_fmac_f32_e32 v16, v144, v80
	v_fmac_f32_e32 v17, v144, v2
	v_fmac_f32_e32 v14, v144, v6
	v_fmac_f32_e32 v15, v144, v10
	v_fmac_f32_e32 v16, v145, v81
	v_fmac_f32_e32 v17, v145, v3
	v_fmac_f32_e32 v14, v145, v7
	v_fmac_f32_e32 v15, v145, v11
	v_fmac_f32_e32 v16, v146, v82
	v_fmac_f32_e32 v17, v146, v4
	v_fmac_f32_e32 v14, v146, v8
	v_fmac_f32_e32 v15, v146, v12
	v_fmac_f32_e32 v16, v147, v83
	v_fmac_f32_e32 v17, v147, v5
	v_fmac_f32_e32 v14, v147, v9
	v_fmac_f32_e32 v15, v147, v13
	ds_read_b128 v[80:83], v54 offset:224
	ds_read_b128 v[2:5], v54 offset:2272
	ds_read_b128 v[6:9], v54 offset:4320
	ds_read_b128 v[10:13], v54 offset:6368
	s_waitcnt lgkmcnt(8)
	v_fmac_f32_e32 v20, v148, v160
	v_fmac_f32_e32 v21, v148, v164
	v_fmac_f32_e32 v18, v148, v168
	v_fmac_f32_e32 v19, v148, v172
	v_fmac_f32_e32 v20, v149, v161
	v_fmac_f32_e32 v21, v149, v165
	v_fmac_f32_e32 v18, v149, v169
	v_fmac_f32_e32 v19, v149, v173
	v_fmac_f32_e32 v20, v150, v162
	v_fmac_f32_e32 v21, v150, v166
	v_fmac_f32_e32 v18, v150, v170
	v_fmac_f32_e32 v19, v150, v174
	v_fmac_f32_e32 v20, v151, v163
	v_fmac_f32_e32 v21, v151, v167
	v_fmac_f32_e32 v18, v151, v171
	v_fmac_f32_e32 v19, v151, v175
	ds_read_b128 v[160:163], v54 offset:8416
	ds_read_b128 v[164:167], v54 offset:10464
	ds_read_b128 v[168:171], v54 offset:12512
	ds_read_b128 v[172:175], v54 offset:14560
	s_waitcnt lgkmcnt(8)
	v_fmac_f32_e32 v16, v148, v64
	v_fmac_f32_e32 v17, v148, v68
	v_fmac_f32_e32 v14, v148, v72
	v_fmac_f32_e32 v15, v148, v76
	v_fmac_f32_e32 v16, v149, v65
	v_fmac_f32_e32 v17, v149, v69
	v_fmac_f32_e32 v14, v149, v73
	v_fmac_f32_e32 v15, v149, v77
	v_fmac_f32_e32 v16, v150, v66
	v_fmac_f32_e32 v17, v150, v70
	v_fmac_f32_e32 v14, v150, v74
	v_fmac_f32_e32 v15, v150, v78
	v_fmac_f32_e32 v16, v151, v67
	v_fmac_f32_e32 v17, v151, v71
	v_fmac_f32_e32 v14, v151, v75
	v_fmac_f32_e32 v15, v151, v79
	ds_read_b128 v[64:67], v54 offset:240
	ds_read_b128 v[68:71], v54 offset:2288
	ds_read_b128 v[72:75], v54 offset:4336
	ds_read_b128 v[76:79], v54 offset:6384
	s_waitcnt lgkmcnt(8)
	v_fmac_f32_e32 v20, v152, v80
	v_fmac_f32_e32 v21, v152, v2
	v_fmac_f32_e32 v18, v152, v6
	v_fmac_f32_e32 v19, v152, v10
	v_fmac_f32_e32 v20, v153, v81
	v_fmac_f32_e32 v21, v153, v3
	v_fmac_f32_e32 v18, v153, v7
	v_fmac_f32_e32 v19, v153, v11
	v_fmac_f32_e32 v20, v154, v82
	v_fmac_f32_e32 v21, v154, v4
	v_fmac_f32_e32 v18, v154, v8
	v_fmac_f32_e32 v19, v154, v12
	v_fmac_f32_e32 v20, v155, v83
	v_fmac_f32_e32 v21, v155, v5
	v_fmac_f32_e32 v18, v155, v9
	v_fmac_f32_e32 v19, v155, v13
	ds_read_b128 v[80:83], v54 offset:8432
	ds_read_b128 v[2:5], v54 offset:10480
	ds_read_b128 v[6:9], v54 offset:12528
	ds_read_b128 v[10:13], v54 offset:14576
	s_waitcnt lgkmcnt(8)
	v_fmac_f32_e32 v16, v152, v160
	v_fmac_f32_e32 v17, v152, v164
	v_fmac_f32_e32 v14, v152, v168
	v_fmac_f32_e32 v15, v152, v172
	v_fmac_f32_e32 v16, v153, v161
	v_fmac_f32_e32 v17, v153, v165
	v_fmac_f32_e32 v14, v153, v169
	v_fmac_f32_e32 v15, v153, v173
	v_fmac_f32_e32 v16, v154, v162
	v_fmac_f32_e32 v17, v154, v166
	v_fmac_f32_e32 v14, v154, v170
	v_fmac_f32_e32 v15, v154, v174
	v_fmac_f32_e32 v16, v155, v163
	v_fmac_f32_e32 v17, v155, v167
	v_fmac_f32_e32 v14, v155, v171
	v_fmac_f32_e32 v15, v155, v175
	s_waitcnt lgkmcnt(4)
	v_fmac_f32_e32 v20, v156, v64
	v_fmac_f32_e32 v21, v156, v68
	v_fmac_f32_e32 v18, v156, v72
	v_fmac_f32_e32 v19, v156, v76
	v_fmac_f32_e32 v20, v157, v65
	v_fmac_f32_e32 v21, v157, v69
	v_fmac_f32_e32 v18, v157, v73
	v_fmac_f32_e32 v19, v157, v77
	v_fmac_f32_e32 v20, v158, v66
	v_fmac_f32_e32 v21, v158, v70
	v_fmac_f32_e32 v18, v158, v74
	v_fmac_f32_e32 v19, v158, v78
	v_fmac_f32_e32 v20, v159, v67
	v_fmac_f32_e32 v21, v159, v71
	v_fmac_f32_e32 v18, v159, v75
	v_fmac_f32_e32 v19, v159, v79
	s_waitcnt lgkmcnt(0)
	v_fmac_f32_e32 v16, v156, v80
	v_fmac_f32_e32 v17, v156, v2
	v_fmac_f32_e32 v14, v156, v6
	v_fmac_f32_e32 v15, v156, v10
	v_fmac_f32_e32 v16, v157, v81
	v_fmac_f32_e32 v17, v157, v3
	v_fmac_f32_e32 v14, v157, v7
	v_fmac_f32_e32 v15, v157, v11
	v_fmac_f32_e32 v16, v158, v82
	v_fmac_f32_e32 v17, v158, v4
	v_fmac_f32_e32 v14, v158, v8
	v_fmac_f32_e32 v15, v158, v12
	v_fmac_f32_e32 v16, v159, v83
	v_fmac_f32_e32 v17, v159, v5
	v_fmac_f32_e32 v14, v159, v9
	v_fmac_f32_e32 v15, v159, v13
	v_readlane_b32 s52, v254, 60
	v_readlane_b32 s53, v254, 61
	v_readlane_b32 s54, v254, 62
	v_readlane_b32 s55, v254, 63
	v_readlane_b32 s56, v255, 0
	v_readlane_b32 s57, v255, 1
	v_readlane_b32 s58, v255, 2
	v_readlane_b32 s59, v255, 3
	v_readlane_b32 s60, v255, 4
	v_readlane_b32 s61, v255, 5
	v_readlane_b32 s62, v255, 6
	v_readlane_b32 s63, v255, 7
	v_readlane_b32 s64, v255, 8
	v_readlane_b32 s65, v255, 9
	v_readlane_b32 s66, v255, 10
	v_readlane_b32 s67, v255, 11
	ds_write2st64_b32 v61, v20, v21 offset0:64 offset1:65
	ds_write2st64_b32 v61, v18, v19 offset0:66 offset1:67
	ds_write2st64_b32 v61, v16, v17 offset0:68 offset1:69
	ds_write2st64_b32 v61, v14, v15 offset0:70 offset1:71
	s_waitcnt lgkmcnt(0)
	s_barrier
	ds_read2st64_b32 v[2:3], v55 offset0:64 offset1:72
	ds_read2st64_b32 v[4:5], v55 offset0:80 offset1:88
	ds_read2st64_b32 v[6:7], v55 offset0:96 offset1:104
	s_cmp_eq_u32 s16, 0
	s_waitcnt lgkmcnt(2)
	v_add_f32_e32 v2, 0, v2
	v_add_f32_e32 v8, v2, v3
	ds_read2st64_b32 v[2:3], v55 offset0:112 offset1:120
	s_waitcnt lgkmcnt(2)
	v_add_f32_e32 v4, v8, v4
	v_add_f32_e32 v4, v4, v5
	s_waitcnt lgkmcnt(1)
	v_add_f32_e32 v4, v4, v6
	v_add_f32_e32 v4, v4, v7
	s_waitcnt lgkmcnt(0)
	v_add_f32_e32 v2, v4, v2
	v_add_f32_e32 v2, v2, v3
	s_cbranch_scc0 .LBB0_420
	v_readlane_b32 s52, v254, 60
	v_readlane_b32 s58, v255, 2
	v_readlane_b32 s59, v255, 3
	v_readlane_b32 s53, v254, 61
	v_readlane_b32 s54, v254, 62
	v_lshl_add_u64 v[4:5], v[46:47], 2, s[58:59]
	global_load_dword v3, v[4:5], off
	v_readlane_b32 s55, v254, 63
	v_readlane_b32 s56, v255, 0
	v_readlane_b32 s57, v255, 1
	v_readlane_b32 s60, v255, 4
	v_readlane_b32 s61, v255, 5
	v_readlane_b32 s62, v255, 6
	v_readlane_b32 s63, v255, 7
	v_readlane_b32 s64, v255, 8
	v_readlane_b32 s65, v255, 9
	v_readlane_b32 s66, v255, 10
	v_readlane_b32 s67, v255, 11
	s_waitcnt vmcnt(0)
	v_add_f32_e32 v2, v2, v3
	s_branch .LBB0_420
